# GEMM k-loops: leading (wr==0) wave half defers its vmcnt(8) wait from before the MMA-opening barrier to after the MMA-closing barrier (lever 1, counted-wait placement)
# speedup vs baseline: 1.0040x; 1.0029x over previous
.LBB0_176:
	s_add_u32 s2, s14, 0xfffc0080
	s_addc_u32 s3, s15, -1
	s_add_i32 s47, 0, 0x10000
	s_cmp_eq_u32 s46, 12
	s_cselect_b32 s25, s7, s3
	s_cselect_b32 s24, s11, s2
	v_add_u32_e32 v0, s47, v155
	s_cselect_b32 s3, s13, s33
	s_cselect_b32 s2, s29, s31
	s_add_i32 s54, 0, 0x14000
	ds_read_b128 v[50:53], v0
	ds_read_b128 v[54:57], v0 offset:1024
	ds_read_b128 v[58:61], v0 offset:2048
	ds_read_b128 v[62:65], v0 offset:3072
	v_add_u32_e32 v0, s54, v155
	ds_read_b128 v[176:179], v0
	ds_read_b128 v[188:191], v0 offset:1024
	ds_read_b128 v[192:195], v0 offset:2048
	ds_read_b128 v[196:199], v0 offset:3072
	v_lshl_add_u64 v[180:181], s[14:15], 0, v[170:171]
	s_add_i32 m0, s90, 0xc000
	ds_read_b128 v[200:203], v186
	ds_read_b128 v[204:207], v186 offset:1024
	ds_read_b128 v[226:229], v186 offset:2048
	ds_read_b128 v[230:233], v186 offset:3072
	ds_read_b128 v[234:237], v186 offset:4096
	ds_read_b128 v[238:241], v186 offset:5120
	ds_read_b128 v[242:245], v186 offset:6144
	ds_read_b128 v[246:249], v186 offset:7168
	global_load_lds_dwordx4 v[180:181], off
	v_lshl_add_u64 v[180:181], s[14:15], 0, v[172:173]
	s_add_i32 m0, s90, 0xe000
	s_nop 0
	global_load_lds_dwordx4 v[180:181], off
	s_and_b64 s[98:99], exec, s[22:23]
	s_cbranch_scc1 .Lvd_0
	s_waitcnt vmcnt(8)
.Lvd_0:
	s_waitcnt lgkmcnt(0)
	s_setprio 1
	s_barrier
	v_mfma_f32_16x16x32_bf16 v[142:145], v[50:53], v[200:203], v[142:145]
	v_mfma_f32_16x16x32_bf16 v[138:141], v[58:61], v[200:203], v[138:141]
	v_mfma_f32_16x16x32_bf16 v[126:129], v[50:53], v[226:229], v[126:129]
	v_mfma_f32_16x16x32_bf16 v[122:125], v[58:61], v[226:229], v[122:125]
	v_mfma_f32_16x16x32_bf16 v[110:113], v[50:53], v[234:237], v[110:113]
	v_mfma_f32_16x16x32_bf16 v[106:109], v[58:61], v[234:237], v[106:109]
	v_mfma_f32_16x16x32_bf16 v[94:97], v[50:53], v[242:245], v[94:97]
	v_mfma_f32_16x16x32_bf16 v[90:93], v[58:61], v[242:245], v[90:93]
	v_mfma_f32_16x16x32_bf16 v[142:145], v[54:57], v[204:207], v[142:145]
	v_mfma_f32_16x16x32_bf16 v[138:141], v[62:65], v[204:207], v[138:141]
	v_mfma_f32_16x16x32_bf16 v[126:129], v[54:57], v[230:233], v[126:129]
	v_mfma_f32_16x16x32_bf16 v[122:125], v[62:65], v[230:233], v[122:125]
	v_mfma_f32_16x16x32_bf16 v[110:113], v[54:57], v[238:241], v[110:113]
	v_mfma_f32_16x16x32_bf16 v[106:109], v[62:65], v[238:241], v[106:109]
	v_mfma_f32_16x16x32_bf16 v[94:97], v[54:57], v[246:249], v[94:97]
	v_mfma_f32_16x16x32_bf16 v[90:93], v[62:65], v[246:249], v[90:93]
	v_mfma_f32_16x16x32_bf16 v[134:137], v[176:179], v[200:203], v[134:137]
	v_mfma_f32_16x16x32_bf16 v[130:133], v[192:195], v[200:203], v[130:133]
	v_mfma_f32_16x16x32_bf16 v[118:121], v[176:179], v[226:229], v[118:121]
	v_mfma_f32_16x16x32_bf16 v[114:117], v[192:195], v[226:229], v[114:117]
	v_mfma_f32_16x16x32_bf16 v[102:105], v[176:179], v[234:237], v[102:105]
	v_mfma_f32_16x16x32_bf16 v[98:101], v[192:195], v[234:237], v[98:101]
	v_mfma_f32_16x16x32_bf16 v[86:89], v[176:179], v[242:245], v[86:89]
	v_mfma_f32_16x16x32_bf16 v[82:85], v[192:195], v[242:245], v[82:85]
	v_mfma_f32_16x16x32_bf16 v[134:137], v[188:191], v[204:207], v[134:137]
	v_mfma_f32_16x16x32_bf16 v[130:133], v[196:199], v[204:207], v[130:133]
	v_mfma_f32_16x16x32_bf16 v[118:121], v[188:191], v[230:233], v[118:121]
	v_mfma_f32_16x16x32_bf16 v[114:117], v[196:199], v[230:233], v[114:117]
	v_mfma_f32_16x16x32_bf16 v[102:105], v[188:191], v[238:241], v[102:105]
	v_mfma_f32_16x16x32_bf16 v[98:101], v[196:199], v[238:241], v[98:101]
	v_mfma_f32_16x16x32_bf16 v[86:89], v[188:191], v[246:249], v[86:89]
	v_mfma_f32_16x16x32_bf16 v[82:85], v[196:199], v[246:249], v[82:85]
	s_barrier
	s_setprio 0
	s_waitcnt vmcnt(8)
	s_add_i32 s47, s47, s42
	v_lshl_add_u64 v[180:181], s[2:3], 0, v[146:147]
	s_mov_b32 m0, s47
	ds_read_b128 v[200:203], v186 offset:16384
	ds_read_b128 v[204:207], v186 offset:17408
	ds_read_b128 v[226:229], v186 offset:18432
	ds_read_b128 v[230:233], v186 offset:19456
	ds_read_b128 v[234:237], v186 offset:20480
	ds_read_b128 v[238:241], v186 offset:21504
	ds_read_b128 v[242:245], v186 offset:22528
	ds_read_b128 v[246:249], v186 offset:23552
	global_load_lds_dwordx4 v[180:181], off
	s_add_i32 m0, s47, 0x2000
	s_add_u32 s58, s2, 0x40000
	v_lshl_add_u64 v[222:223], s[2:3], 0, v[148:149]
	s_addc_u32 s59, s3, 0
	s_add_i32 s47, s54, s42
	global_load_lds_dwordx4 v[222:223], off
	v_lshl_add_u64 v[224:225], s[58:59], 0, v[146:147]
	s_mov_b32 m0, s47
	v_lshl_add_u64 v[250:251], s[24:25], 0, v[148:149]
	global_load_lds_dwordx4 v[224:225], off
	v_lshl_add_u64 v[224:225], s[58:59], 0, v[148:149]
	s_add_i32 m0, s47, 0x2000
	s_nop 0
	global_load_lds_dwordx4 v[224:225], off
	v_lshl_add_u64 v[224:225], s[24:25], 0, v[146:147]
	s_mov_b32 m0, s90
	s_nop 0
	global_load_lds_dwordx4 v[224:225], off
	s_mov_b32 m0, s91
	s_nop 0
	global_load_lds_dwordx4 v[250:251], off
	s_and_b64 s[98:99], exec, s[22:23]
	s_cbranch_scc1 .Lvd_1
	s_waitcnt vmcnt(8)
.Lvd_1:
	s_waitcnt lgkmcnt(0)
	s_setprio 1
	s_barrier
	v_mfma_f32_16x16x32_bf16 v[78:81], v[50:53], v[200:203], v[78:81]
	v_mfma_f32_16x16x32_bf16 v[74:77], v[58:61], v[200:203], v[74:77]
	v_mfma_f32_16x16x32_bf16 v[46:49], v[50:53], v[226:229], v[46:49]
	v_mfma_f32_16x16x32_bf16 v[42:45], v[58:61], v[226:229], v[42:45]
	v_mfma_f32_16x16x32_bf16 v[30:33], v[50:53], v[234:237], v[30:33]
	v_mfma_f32_16x16x32_bf16 v[26:29], v[58:61], v[234:237], v[26:29]
	v_mfma_f32_16x16x32_bf16 v[14:17], v[50:53], v[242:245], v[14:17]
	v_mfma_f32_16x16x32_bf16 v[10:13], v[58:61], v[242:245], v[10:13]
	v_mfma_f32_16x16x32_bf16 v[78:81], v[54:57], v[204:207], v[78:81]
	v_mfma_f32_16x16x32_bf16 v[74:77], v[62:65], v[204:207], v[74:77]
	v_mfma_f32_16x16x32_bf16 v[46:49], v[54:57], v[230:233], v[46:49]
	v_mfma_f32_16x16x32_bf16 v[42:45], v[62:65], v[230:233], v[42:45]
	v_mfma_f32_16x16x32_bf16 v[30:33], v[54:57], v[238:241], v[30:33]
	v_mfma_f32_16x16x32_bf16 v[26:29], v[62:65], v[238:241], v[26:29]
	v_mfma_f32_16x16x32_bf16 v[14:17], v[54:57], v[246:249], v[14:17]
	v_mfma_f32_16x16x32_bf16 v[10:13], v[62:65], v[246:249], v[10:13]
	v_mfma_f32_16x16x32_bf16 v[38:41], v[176:179], v[226:229], v[38:41]
	v_mfma_f32_16x16x32_bf16 v[34:37], v[192:195], v[226:229], v[34:37]
	v_mfma_f32_16x16x32_bf16 v[22:25], v[176:179], v[234:237], v[22:25]
	v_mfma_f32_16x16x32_bf16 v[18:21], v[192:195], v[234:237], v[18:21]
	v_mfma_f32_16x16x32_bf16 v[6:9], v[176:179], v[242:245], v[6:9]
	v_mfma_f32_16x16x32_bf16 v[2:5], v[192:195], v[242:245], v[2:5]
	v_mfma_f32_16x16x32_bf16 v[50:53], v[176:179], v[200:203], v[70:73]
	v_mfma_f32_16x16x32_bf16 v[54:57], v[192:195], v[200:203], v[66:69]
	v_mfma_f32_16x16x32_bf16 v[38:41], v[188:191], v[230:233], v[38:41]
	v_mfma_f32_16x16x32_bf16 v[34:37], v[196:199], v[230:233], v[34:37]
	v_mfma_f32_16x16x32_bf16 v[22:25], v[188:191], v[238:241], v[22:25]
	v_mfma_f32_16x16x32_bf16 v[18:21], v[196:199], v[238:241], v[18:21]
	v_mfma_f32_16x16x32_bf16 v[6:9], v[188:191], v[246:249], v[6:9]
	v_mfma_f32_16x16x32_bf16 v[2:5], v[196:199], v[246:249], v[2:5]
	v_mfma_f32_16x16x32_bf16 v[50:53], v[188:191], v[204:207], v[50:53]
	v_mfma_f32_16x16x32_bf16 v[54:57], v[196:199], v[204:207], v[54:57]
	s_barrier
	s_setprio 0
	s_waitcnt vmcnt(8)
	s_add_i32 s47, 0, 0x18000
	v_add_u32_e32 v0, s47, v155
	s_add_i32 s54, 0, 0x1c000
	ds_read_b128 v[58:61], v0
	ds_read_b128 v[62:65], v0 offset:1024
	ds_read_b128 v[66:69], v0 offset:2048
	ds_read_b128 v[70:73], v0 offset:3072
	v_add_u32_e32 v0, s54, v155
	ds_read_b128 v[176:179], v0
	ds_read_b128 v[188:191], v0 offset:1024
	ds_read_b128 v[192:195], v0 offset:2048
	ds_read_b128 v[196:199], v0 offset:3072
	s_add_u32 s24, s24, 0x40000
	s_addc_u32 s25, s25, 0
	s_mov_b32 m0, s74
	v_lshl_add_u64 v[218:219], s[24:25], 0, v[146:147]
	ds_read_b128 v[200:203], v186 offset:32768
	ds_read_b128 v[204:207], v186 offset:33792
	ds_read_b128 v[226:229], v186 offset:34816
	ds_read_b128 v[230:233], v186 offset:35840
	ds_read_b128 v[234:237], v186 offset:36864
	ds_read_b128 v[238:241], v186 offset:37888
	ds_read_b128 v[242:245], v186 offset:38912
	ds_read_b128 v[246:249], v186 offset:39936
	global_load_lds_dwordx4 v[218:219], off
	v_lshl_add_u64 v[218:219], s[24:25], 0, v[148:149]
	s_mov_b32 m0, s75
	s_nop 0
	global_load_lds_dwordx4 v[218:219], off
	s_and_b64 s[98:99], exec, s[22:23]
	s_cbranch_scc1 .Lvd_2
	s_waitcnt vmcnt(8)
.Lvd_2:
	s_waitcnt lgkmcnt(0)
	s_setprio 1
	s_barrier
	v_mfma_f32_16x16x32_bf16 v[142:145], v[58:61], v[200:203], v[142:145]
	v_mfma_f32_16x16x32_bf16 v[138:141], v[66:69], v[200:203], v[138:141]
	v_mfma_f32_16x16x32_bf16 v[126:129], v[58:61], v[226:229], v[126:129]
	v_mfma_f32_16x16x32_bf16 v[122:125], v[66:69], v[226:229], v[122:125]
	v_mfma_f32_16x16x32_bf16 v[110:113], v[58:61], v[234:237], v[110:113]
	v_mfma_f32_16x16x32_bf16 v[106:109], v[66:69], v[234:237], v[106:109]
	v_mfma_f32_16x16x32_bf16 v[94:97], v[58:61], v[242:245], v[94:97]
	v_mfma_f32_16x16x32_bf16 v[90:93], v[66:69], v[242:245], v[90:93]
	v_mfma_f32_16x16x32_bf16 v[142:145], v[62:65], v[204:207], v[142:145]
	v_mfma_f32_16x16x32_bf16 v[138:141], v[70:73], v[204:207], v[138:141]
	v_mfma_f32_16x16x32_bf16 v[126:129], v[62:65], v[230:233], v[126:129]
	v_mfma_f32_16x16x32_bf16 v[122:125], v[70:73], v[230:233], v[122:125]
	v_mfma_f32_16x16x32_bf16 v[110:113], v[62:65], v[238:241], v[110:113]
	v_mfma_f32_16x16x32_bf16 v[106:109], v[70:73], v[238:241], v[106:109]
	v_mfma_f32_16x16x32_bf16 v[94:97], v[62:65], v[246:249], v[94:97]
	v_mfma_f32_16x16x32_bf16 v[90:93], v[70:73], v[246:249], v[90:93]
	v_mfma_f32_16x16x32_bf16 v[134:137], v[176:179], v[200:203], v[134:137]
	v_mfma_f32_16x16x32_bf16 v[130:133], v[192:195], v[200:203], v[130:133]
	v_mfma_f32_16x16x32_bf16 v[118:121], v[176:179], v[226:229], v[118:121]
	v_mfma_f32_16x16x32_bf16 v[114:117], v[192:195], v[226:229], v[114:117]
	v_mfma_f32_16x16x32_bf16 v[102:105], v[176:179], v[234:237], v[102:105]
	v_mfma_f32_16x16x32_bf16 v[98:101], v[192:195], v[234:237], v[98:101]
	v_mfma_f32_16x16x32_bf16 v[86:89], v[176:179], v[242:245], v[86:89]
	v_mfma_f32_16x16x32_bf16 v[82:85], v[192:195], v[242:245], v[82:85]
	v_mfma_f32_16x16x32_bf16 v[134:137], v[188:191], v[204:207], v[134:137]
	v_mfma_f32_16x16x32_bf16 v[130:133], v[196:199], v[204:207], v[130:133]
	v_mfma_f32_16x16x32_bf16 v[118:121], v[188:191], v[230:233], v[118:121]
	v_mfma_f32_16x16x32_bf16 v[114:117], v[196:199], v[230:233], v[114:117]
	v_mfma_f32_16x16x32_bf16 v[102:105], v[188:191], v[238:241], v[102:105]
	v_mfma_f32_16x16x32_bf16 v[98:101], v[196:199], v[238:241], v[98:101]
	v_mfma_f32_16x16x32_bf16 v[86:89], v[188:191], v[246:249], v[86:89]
	v_mfma_f32_16x16x32_bf16 v[82:85], v[196:199], v[246:249], v[82:85]
	s_barrier
	s_setprio 0
	s_waitcnt vmcnt(8)
	s_add_i32 s24, s47, s42
	v_lshl_add_u64 v[180:181], v[180:181], 0, s[44:45]
	s_mov_b32 m0, s24
	ds_read_b128 v[200:203], v186 offset:49152
	ds_read_b128 v[204:207], v186 offset:50176
	ds_read_b128 v[226:229], v186 offset:51200
	ds_read_b128 v[230:233], v186 offset:52224
	ds_read_b128 v[234:237], v186 offset:53248
	ds_read_b128 v[238:241], v186 offset:54272
	ds_read_b128 v[242:245], v186 offset:55296
	ds_read_b128 v[246:249], v186 offset:56320
	global_load_lds_dwordx4 v[180:181], off
	s_add_i32 m0, s24, 0x2000
	s_add_u32 s2, s2, 0x40080
	v_lshl_add_u64 v[180:181], v[222:223], 0, s[44:45]
	s_addc_u32 s3, s3, 0
	s_add_i32 s24, s54, s42
	global_load_lds_dwordx4 v[180:181], off
	v_lshl_add_u64 v[180:181], s[2:3], 0, v[146:147]
	s_mov_b32 m0, s24
	s_nop 0
	global_load_lds_dwordx4 v[180:181], off
	v_lshl_add_u64 v[180:181], s[2:3], 0, v[148:149]
	s_add_i32 m0, s24, 0x2000
	s_nop 0
	global_load_lds_dwordx4 v[180:181], off
	v_lshl_add_u64 v[180:181], v[224:225], 0, s[44:45]
	s_mov_b32 m0, s20
	s_nop 0
	global_load_lds_dwordx4 v[180:181], off
	v_lshl_add_u64 v[180:181], v[250:251], 0, s[44:45]
	s_mov_b32 m0, s21
	s_nop 0
	global_load_lds_dwordx4 v[180:181], off
	s_and_b64 s[98:99], exec, s[22:23]
	s_cbranch_scc1 .Lvd_3
	s_waitcnt vmcnt(8)
.Lvd_3:
	s_waitcnt lgkmcnt(0)
	s_setprio 1
	s_barrier
	v_mfma_f32_16x16x32_bf16 v[78:81], v[58:61], v[200:203], v[78:81]
	v_mfma_f32_16x16x32_bf16 v[74:77], v[66:69], v[200:203], v[74:77]
	v_mfma_f32_16x16x32_bf16 v[46:49], v[58:61], v[226:229], v[46:49]
	v_mfma_f32_16x16x32_bf16 v[42:45], v[66:69], v[226:229], v[42:45]
	v_mfma_f32_16x16x32_bf16 v[30:33], v[58:61], v[234:237], v[30:33]
	v_mfma_f32_16x16x32_bf16 v[26:29], v[66:69], v[234:237], v[26:29]
	v_mfma_f32_16x16x32_bf16 v[14:17], v[58:61], v[242:245], v[14:17]
	v_mfma_f32_16x16x32_bf16 v[10:13], v[66:69], v[242:245], v[10:13]
	v_mfma_f32_16x16x32_bf16 v[78:81], v[62:65], v[204:207], v[78:81]
	v_mfma_f32_16x16x32_bf16 v[74:77], v[70:73], v[204:207], v[74:77]
	v_mfma_f32_16x16x32_bf16 v[46:49], v[62:65], v[230:233], v[46:49]
	v_mfma_f32_16x16x32_bf16 v[42:45], v[70:73], v[230:233], v[42:45]
	v_mfma_f32_16x16x32_bf16 v[30:33], v[62:65], v[238:241], v[30:33]
	v_mfma_f32_16x16x32_bf16 v[26:29], v[70:73], v[238:241], v[26:29]
	v_mfma_f32_16x16x32_bf16 v[14:17], v[62:65], v[246:249], v[14:17]
	v_mfma_f32_16x16x32_bf16 v[10:13], v[70:73], v[246:249], v[10:13]
	v_mfma_f32_16x16x32_bf16 v[50:53], v[176:179], v[200:203], v[50:53]
	v_mfma_f32_16x16x32_bf16 v[70:73], v[188:191], v[204:207], v[50:53]
	v_mfma_f32_16x16x32_bf16 v[50:53], v[192:195], v[200:203], v[54:57]
	v_mfma_f32_16x16x32_bf16 v[38:41], v[176:179], v[226:229], v[38:41]
	v_mfma_f32_16x16x32_bf16 v[34:37], v[192:195], v[226:229], v[34:37]
	v_mfma_f32_16x16x32_bf16 v[22:25], v[176:179], v[234:237], v[22:25]
	v_mfma_f32_16x16x32_bf16 v[18:21], v[192:195], v[234:237], v[18:21]
	v_mfma_f32_16x16x32_bf16 v[6:9], v[176:179], v[242:245], v[6:9]
	v_mfma_f32_16x16x32_bf16 v[2:5], v[192:195], v[242:245], v[2:5]
	v_mfma_f32_16x16x32_bf16 v[66:69], v[196:199], v[204:207], v[50:53]
	v_mfma_f32_16x16x32_bf16 v[38:41], v[188:191], v[230:233], v[38:41]
	v_mfma_f32_16x16x32_bf16 v[34:37], v[196:199], v[230:233], v[34:37]
	v_mfma_f32_16x16x32_bf16 v[22:25], v[188:191], v[238:241], v[22:25]
	v_mfma_f32_16x16x32_bf16 v[18:21], v[196:199], v[238:241], v[18:21]
	v_mfma_f32_16x16x32_bf16 v[6:9], v[188:191], v[246:249], v[6:9]
	v_mfma_f32_16x16x32_bf16 v[2:5], v[196:199], v[246:249], v[2:5]
	s_barrier
	s_setprio 0
	s_waitcnt vmcnt(8)
	s_add_i32 s46, s46, 2
	s_add_u32 s14, s14, 0x100
	s_addc_u32 s15, s15, 0
	s_add_u32 s31, s31, 0x100
	s_addc_u32 s33, s33, 0
	s_cmp_gt_u32 s46, 13
	s_cbranch_scc0 .LBB0_176
	s_and_b64 vcc, exec, s[22:23]
	s_cbranch_vccz .LBB0_179
	s_barrier

.LBB0_650:
	s_add_u32 s2, s4, 0x100
	s_addc_u32 s3, s5, 0
	s_add_i32 s49, 0, 0x10000
	s_cmp_eq_u32 s48, 12
	s_cselect_b32 s29, s17, s3
	s_cselect_b32 s28, s25, s2
	v_add_u32_e32 v0, s49, v135
	s_cselect_b32 s27, s15, s47
	s_cselect_b32 s26, s42, s46
	s_add_i32 s50, 0, 0x14000
	ds_read_b128 v[146:149], v0
	ds_read_b128 v[150:153], v0 offset:1024
	ds_read_b128 v[154:157], v0 offset:2048
	ds_read_b128 v[158:161], v0 offset:3072
	v_add_u32_e32 v0, s50, v135
	ds_read_b128 v[162:165], v0
	ds_read_b128 v[166:169], v0 offset:1024
	ds_read_b128 v[170:173], v0 offset:2048
	ds_read_b128 v[174:177], v0 offset:3072
	v_lshl_add_u64 v[142:143], s[4:5], 0, v[138:139]
	s_add_i32 m0, s23, 0xc000
	ds_read_b128 v[178:181], v144
	ds_read_b128 v[182:185], v144 offset:1024
	ds_read_b128 v[186:189], v144 offset:2048
	ds_read_b128 v[190:193], v144 offset:3072
	ds_read_b128 v[194:197], v144 offset:4096
	ds_read_b128 v[198:201], v144 offset:5120
	ds_read_b128 v[202:205], v144 offset:6144
	ds_read_b128 v[222:225], v144 offset:7168
	global_load_lds_dwordx4 v[142:143], off
	v_lshl_add_u64 v[142:143], s[4:5], 0, v[140:141]
	s_add_i32 m0, s23, 0xe000
	s_nop 0
	global_load_lds_dwordx4 v[142:143], off
	s_and_b64 s[98:99], exec, s[12:13]
	s_cbranch_scc1 .Lvd_4
	s_waitcnt vmcnt(8)
.Lvd_4:
	s_waitcnt lgkmcnt(0)
	s_setprio 1
	s_barrier
	v_mfma_f32_16x16x32_bf16 v[126:129], v[146:149], v[178:181], v[126:129]
	v_mfma_f32_16x16x32_bf16 v[122:125], v[154:157], v[178:181], v[122:125]
	v_mfma_f32_16x16x32_bf16 v[110:113], v[146:149], v[186:189], v[110:113]
	v_mfma_f32_16x16x32_bf16 v[106:109], v[154:157], v[186:189], v[106:109]
	v_mfma_f32_16x16x32_bf16 v[94:97], v[146:149], v[194:197], v[94:97]
	v_mfma_f32_16x16x32_bf16 v[90:93], v[154:157], v[194:197], v[90:93]
	v_mfma_f32_16x16x32_bf16 v[78:81], v[146:149], v[202:205], v[78:81]
	v_mfma_f32_16x16x32_bf16 v[74:77], v[154:157], v[202:205], v[74:77]
	v_mfma_f32_16x16x32_bf16 v[126:129], v[150:153], v[182:185], v[126:129]
	v_mfma_f32_16x16x32_bf16 v[122:125], v[158:161], v[182:185], v[122:125]
	v_mfma_f32_16x16x32_bf16 v[110:113], v[150:153], v[190:193], v[110:113]
	v_mfma_f32_16x16x32_bf16 v[106:109], v[158:161], v[190:193], v[106:109]
	v_mfma_f32_16x16x32_bf16 v[94:97], v[150:153], v[198:201], v[94:97]
	v_mfma_f32_16x16x32_bf16 v[90:93], v[158:161], v[198:201], v[90:93]
	v_mfma_f32_16x16x32_bf16 v[78:81], v[150:153], v[222:225], v[78:81]
	v_mfma_f32_16x16x32_bf16 v[74:77], v[158:161], v[222:225], v[74:77]
	v_mfma_f32_16x16x32_bf16 v[118:121], v[162:165], v[178:181], v[118:121]
	v_mfma_f32_16x16x32_bf16 v[114:117], v[170:173], v[178:181], v[114:117]
	v_mfma_f32_16x16x32_bf16 v[102:105], v[162:165], v[186:189], v[102:105]
	v_mfma_f32_16x16x32_bf16 v[98:101], v[170:173], v[186:189], v[98:101]
	v_mfma_f32_16x16x32_bf16 v[86:89], v[162:165], v[194:197], v[86:89]
	v_mfma_f32_16x16x32_bf16 v[82:85], v[170:173], v[194:197], v[82:85]
	v_mfma_f32_16x16x32_bf16 v[70:73], v[162:165], v[202:205], v[70:73]
	v_mfma_f32_16x16x32_bf16 v[66:69], v[170:173], v[202:205], v[66:69]
	v_mfma_f32_16x16x32_bf16 v[118:121], v[166:169], v[182:185], v[118:121]
	v_mfma_f32_16x16x32_bf16 v[114:117], v[174:177], v[182:185], v[114:117]
	v_mfma_f32_16x16x32_bf16 v[102:105], v[166:169], v[190:193], v[102:105]
	v_mfma_f32_16x16x32_bf16 v[98:101], v[174:177], v[190:193], v[98:101]
	v_mfma_f32_16x16x32_bf16 v[86:89], v[166:169], v[198:201], v[86:89]
	v_mfma_f32_16x16x32_bf16 v[82:85], v[174:177], v[198:201], v[82:85]
	v_mfma_f32_16x16x32_bf16 v[70:73], v[166:169], v[222:225], v[70:73]
	v_mfma_f32_16x16x32_bf16 v[66:69], v[174:177], v[222:225], v[66:69]
	s_barrier
	s_setprio 0
	s_waitcnt vmcnt(8)
	s_add_i32 s4, s49, s30
	v_lshl_add_u64 v[142:143], s[26:27], 0, v[130:131]
	s_mov_b32 m0, s4
	ds_read_b128 v[178:181], v144 offset:16384
	ds_read_b128 v[182:185], v144 offset:17408
	ds_read_b128 v[186:189], v144 offset:18432
	ds_read_b128 v[190:193], v144 offset:19456
	ds_read_b128 v[194:197], v144 offset:20480
	ds_read_b128 v[198:201], v144 offset:21504
	ds_read_b128 v[202:205], v144 offset:22528
	ds_read_b128 v[222:225], v144 offset:23552
	global_load_lds_dwordx4 v[142:143], off
	s_add_i32 m0, s4, 0x2000
	s_add_u32 s4, s26, 0x40000
	v_lshl_add_u64 v[206:207], s[26:27], 0, v[132:133]
	s_addc_u32 s5, s27, 0
	s_add_i32 s49, s50, s30
	global_load_lds_dwordx4 v[206:207], off
	v_lshl_add_u64 v[218:219], s[4:5], 0, v[130:131]
	s_mov_b32 m0, s49
	v_lshl_add_u64 v[226:227], s[28:29], 0, v[132:133]
	global_load_lds_dwordx4 v[218:219], off
	v_lshl_add_u64 v[218:219], s[4:5], 0, v[132:133]
	s_add_i32 m0, s49, 0x2000
	s_nop 0
	global_load_lds_dwordx4 v[218:219], off
	v_lshl_add_u64 v[218:219], s[28:29], 0, v[130:131]
	s_mov_b32 m0, s23
	s_nop 0
	global_load_lds_dwordx4 v[218:219], off
	s_mov_b32 m0, s31
	s_nop 0
	global_load_lds_dwordx4 v[226:227], off
	s_and_b64 s[98:99], exec, s[12:13]
	s_cbranch_scc1 .Lvd_5
	s_waitcnt vmcnt(8)
.Lvd_5:
	s_waitcnt lgkmcnt(0)
	s_setprio 1
	s_barrier
	v_mfma_f32_16x16x32_bf16 v[62:65], v[146:149], v[178:181], v[62:65]
	v_mfma_f32_16x16x32_bf16 v[58:61], v[154:157], v[178:181], v[58:61]
	v_mfma_f32_16x16x32_bf16 v[46:49], v[146:149], v[186:189], v[46:49]
	v_mfma_f32_16x16x32_bf16 v[42:45], v[154:157], v[186:189], v[42:45]
	v_mfma_f32_16x16x32_bf16 v[30:33], v[146:149], v[194:197], v[30:33]
	v_mfma_f32_16x16x32_bf16 v[26:29], v[154:157], v[194:197], v[26:29]
	v_mfma_f32_16x16x32_bf16 v[14:17], v[146:149], v[202:205], v[14:17]
	v_mfma_f32_16x16x32_bf16 v[10:13], v[154:157], v[202:205], v[10:13]
	v_mfma_f32_16x16x32_bf16 v[62:65], v[150:153], v[182:185], v[62:65]
	v_mfma_f32_16x16x32_bf16 v[58:61], v[158:161], v[182:185], v[58:61]
	v_mfma_f32_16x16x32_bf16 v[46:49], v[150:153], v[190:193], v[46:49]
	v_mfma_f32_16x16x32_bf16 v[42:45], v[158:161], v[190:193], v[42:45]
	v_mfma_f32_16x16x32_bf16 v[30:33], v[150:153], v[198:201], v[30:33]
	v_mfma_f32_16x16x32_bf16 v[26:29], v[158:161], v[198:201], v[26:29]
	v_mfma_f32_16x16x32_bf16 v[14:17], v[150:153], v[222:225], v[14:17]
	v_mfma_f32_16x16x32_bf16 v[10:13], v[158:161], v[222:225], v[10:13]
	v_mfma_f32_16x16x32_bf16 v[54:57], v[162:165], v[178:181], v[54:57]
	v_mfma_f32_16x16x32_bf16 v[50:53], v[170:173], v[178:181], v[50:53]
	v_mfma_f32_16x16x32_bf16 v[38:41], v[162:165], v[186:189], v[38:41]
	v_mfma_f32_16x16x32_bf16 v[34:37], v[170:173], v[186:189], v[34:37]
	v_mfma_f32_16x16x32_bf16 v[22:25], v[162:165], v[194:197], v[22:25]
	v_mfma_f32_16x16x32_bf16 v[18:21], v[170:173], v[194:197], v[18:21]
	v_mfma_f32_16x16x32_bf16 v[6:9], v[162:165], v[202:205], v[6:9]
	v_mfma_f32_16x16x32_bf16 v[2:5], v[170:173], v[202:205], v[2:5]
	v_mfma_f32_16x16x32_bf16 v[54:57], v[166:169], v[182:185], v[54:57]
	v_mfma_f32_16x16x32_bf16 v[50:53], v[174:177], v[182:185], v[50:53]
	v_mfma_f32_16x16x32_bf16 v[38:41], v[166:169], v[190:193], v[38:41]
	v_mfma_f32_16x16x32_bf16 v[34:37], v[174:177], v[190:193], v[34:37]
	v_mfma_f32_16x16x32_bf16 v[22:25], v[166:169], v[198:201], v[22:25]
	v_mfma_f32_16x16x32_bf16 v[18:21], v[174:177], v[198:201], v[18:21]
	v_mfma_f32_16x16x32_bf16 v[6:9], v[166:169], v[222:225], v[6:9]
	v_mfma_f32_16x16x32_bf16 v[2:5], v[174:177], v[222:225], v[2:5]
	s_barrier
	s_setprio 0
	s_waitcnt vmcnt(8)
	s_add_i32 s49, 0, 0x18000
	v_add_u32_e32 v0, s49, v135
	s_add_i32 s50, 0, 0x1c000
	ds_read_b128 v[146:149], v0
	ds_read_b128 v[150:153], v0 offset:1024
	ds_read_b128 v[154:157], v0 offset:2048
	ds_read_b128 v[158:161], v0 offset:3072
	v_add_u32_e32 v0, s50, v135
	ds_read_b128 v[162:165], v0
	ds_read_b128 v[166:169], v0 offset:1024
	ds_read_b128 v[170:173], v0 offset:2048
	ds_read_b128 v[174:177], v0 offset:3072
	s_add_u32 s4, s28, 0x40000
	s_addc_u32 s5, s29, 0
	s_mov_b32 m0, s33
	v_lshl_add_u64 v[228:229], s[4:5], 0, v[130:131]
	ds_read_b128 v[178:181], v144 offset:32768
	ds_read_b128 v[182:185], v144 offset:33792
	ds_read_b128 v[186:189], v144 offset:34816
	ds_read_b128 v[190:193], v144 offset:35840
	ds_read_b128 v[194:197], v144 offset:36864
	ds_read_b128 v[198:201], v144 offset:37888
	ds_read_b128 v[202:205], v144 offset:38912
	ds_read_b128 v[222:225], v144 offset:39936
	global_load_lds_dwordx4 v[228:229], off
	v_lshl_add_u64 v[228:229], s[4:5], 0, v[132:133]
	s_mov_b32 m0, s34
	s_nop 0
	global_load_lds_dwordx4 v[228:229], off
	s_and_b64 s[98:99], exec, s[12:13]
	s_cbranch_scc1 .Lvd_6
	s_waitcnt vmcnt(8)
.Lvd_6:
	s_waitcnt lgkmcnt(0)
	s_setprio 1
	s_barrier
	v_mfma_f32_16x16x32_bf16 v[126:129], v[146:149], v[178:181], v[126:129]
	v_mfma_f32_16x16x32_bf16 v[122:125], v[154:157], v[178:181], v[122:125]
	v_mfma_f32_16x16x32_bf16 v[110:113], v[146:149], v[186:189], v[110:113]
	v_mfma_f32_16x16x32_bf16 v[106:109], v[154:157], v[186:189], v[106:109]
	v_mfma_f32_16x16x32_bf16 v[94:97], v[146:149], v[194:197], v[94:97]
	v_mfma_f32_16x16x32_bf16 v[90:93], v[154:157], v[194:197], v[90:93]
	v_mfma_f32_16x16x32_bf16 v[78:81], v[146:149], v[202:205], v[78:81]
	v_mfma_f32_16x16x32_bf16 v[74:77], v[154:157], v[202:205], v[74:77]
	v_mfma_f32_16x16x32_bf16 v[126:129], v[150:153], v[182:185], v[126:129]
	v_mfma_f32_16x16x32_bf16 v[122:125], v[158:161], v[182:185], v[122:125]
	v_mfma_f32_16x16x32_bf16 v[110:113], v[150:153], v[190:193], v[110:113]
	v_mfma_f32_16x16x32_bf16 v[106:109], v[158:161], v[190:193], v[106:109]
	v_mfma_f32_16x16x32_bf16 v[94:97], v[150:153], v[198:201], v[94:97]
	v_mfma_f32_16x16x32_bf16 v[90:93], v[158:161], v[198:201], v[90:93]
	v_mfma_f32_16x16x32_bf16 v[78:81], v[150:153], v[222:225], v[78:81]
	v_mfma_f32_16x16x32_bf16 v[74:77], v[158:161], v[222:225], v[74:77]
	v_mfma_f32_16x16x32_bf16 v[118:121], v[162:165], v[178:181], v[118:121]
	v_mfma_f32_16x16x32_bf16 v[114:117], v[170:173], v[178:181], v[114:117]
	v_mfma_f32_16x16x32_bf16 v[102:105], v[162:165], v[186:189], v[102:105]
	v_mfma_f32_16x16x32_bf16 v[98:101], v[170:173], v[186:189], v[98:101]
	v_mfma_f32_16x16x32_bf16 v[86:89], v[162:165], v[194:197], v[86:89]
	v_mfma_f32_16x16x32_bf16 v[82:85], v[170:173], v[194:197], v[82:85]
	v_mfma_f32_16x16x32_bf16 v[70:73], v[162:165], v[202:205], v[70:73]
	v_mfma_f32_16x16x32_bf16 v[66:69], v[170:173], v[202:205], v[66:69]
	v_mfma_f32_16x16x32_bf16 v[118:121], v[166:169], v[182:185], v[118:121]
	v_mfma_f32_16x16x32_bf16 v[114:117], v[174:177], v[182:185], v[114:117]
	v_mfma_f32_16x16x32_bf16 v[102:105], v[166:169], v[190:193], v[102:105]
	v_mfma_f32_16x16x32_bf16 v[98:101], v[174:177], v[190:193], v[98:101]
	v_mfma_f32_16x16x32_bf16 v[86:89], v[166:169], v[198:201], v[86:89]
	v_mfma_f32_16x16x32_bf16 v[82:85], v[174:177], v[198:201], v[82:85]
	v_mfma_f32_16x16x32_bf16 v[70:73], v[166:169], v[222:225], v[70:73]
	v_mfma_f32_16x16x32_bf16 v[66:69], v[174:177], v[222:225], v[66:69]
	s_barrier
	s_setprio 0
	s_waitcnt vmcnt(8)
	s_add_i32 s4, s49, s30
	v_lshl_add_u64 v[142:143], v[142:143], 0, s[44:45]
	s_mov_b32 m0, s4
	ds_read_b128 v[178:181], v144 offset:49152
	ds_read_b128 v[182:185], v144 offset:50176
	ds_read_b128 v[186:189], v144 offset:51200
	ds_read_b128 v[190:193], v144 offset:52224
	ds_read_b128 v[194:197], v144 offset:53248
	ds_read_b128 v[198:201], v144 offset:54272
	ds_read_b128 v[202:205], v144 offset:55296
	ds_read_b128 v[222:225], v144 offset:56320
	global_load_lds_dwordx4 v[142:143], off
	s_add_i32 m0, s4, 0x2000
	s_add_u32 s4, s26, 0x40080
	v_lshl_add_u64 v[142:143], v[206:207], 0, s[44:45]
	s_addc_u32 s5, s27, 0
	s_add_i32 s26, s50, s30
	global_load_lds_dwordx4 v[142:143], off
	v_lshl_add_u64 v[142:143], s[4:5], 0, v[130:131]
	s_mov_b32 m0, s26
	s_nop 0
	global_load_lds_dwordx4 v[142:143], off
	v_lshl_add_u64 v[142:143], s[4:5], 0, v[132:133]
	s_add_i32 m0, s26, 0x2000
	s_nop 0
	global_load_lds_dwordx4 v[142:143], off
	v_lshl_add_u64 v[142:143], v[218:219], 0, s[44:45]
	s_mov_b32 m0, s37
	s_nop 0
	global_load_lds_dwordx4 v[142:143], off
	v_lshl_add_u64 v[142:143], v[226:227], 0, s[44:45]
	s_mov_b32 m0, s38
	s_nop 0
	global_load_lds_dwordx4 v[142:143], off
	s_and_b64 s[98:99], exec, s[12:13]
	s_cbranch_scc1 .Lvd_7
	s_waitcnt vmcnt(8)
.Lvd_7:
	s_waitcnt lgkmcnt(0)
	s_setprio 1
	s_barrier
	v_mfma_f32_16x16x32_bf16 v[62:65], v[146:149], v[178:181], v[62:65]
	v_mfma_f32_16x16x32_bf16 v[58:61], v[154:157], v[178:181], v[58:61]
	v_mfma_f32_16x16x32_bf16 v[46:49], v[146:149], v[186:189], v[46:49]
	v_mfma_f32_16x16x32_bf16 v[42:45], v[154:157], v[186:189], v[42:45]
	v_mfma_f32_16x16x32_bf16 v[30:33], v[146:149], v[194:197], v[30:33]
	v_mfma_f32_16x16x32_bf16 v[26:29], v[154:157], v[194:197], v[26:29]
	v_mfma_f32_16x16x32_bf16 v[14:17], v[146:149], v[202:205], v[14:17]
	v_mfma_f32_16x16x32_bf16 v[10:13], v[154:157], v[202:205], v[10:13]
	v_mfma_f32_16x16x32_bf16 v[62:65], v[150:153], v[182:185], v[62:65]
	v_mfma_f32_16x16x32_bf16 v[58:61], v[158:161], v[182:185], v[58:61]
	v_mfma_f32_16x16x32_bf16 v[46:49], v[150:153], v[190:193], v[46:49]
	v_mfma_f32_16x16x32_bf16 v[42:45], v[158:161], v[190:193], v[42:45]
	v_mfma_f32_16x16x32_bf16 v[30:33], v[150:153], v[198:201], v[30:33]
	v_mfma_f32_16x16x32_bf16 v[26:29], v[158:161], v[198:201], v[26:29]
	v_mfma_f32_16x16x32_bf16 v[14:17], v[150:153], v[222:225], v[14:17]
	v_mfma_f32_16x16x32_bf16 v[10:13], v[158:161], v[222:225], v[10:13]
	v_mfma_f32_16x16x32_bf16 v[54:57], v[162:165], v[178:181], v[54:57]
	v_mfma_f32_16x16x32_bf16 v[50:53], v[170:173], v[178:181], v[50:53]
	v_mfma_f32_16x16x32_bf16 v[38:41], v[162:165], v[186:189], v[38:41]
	v_mfma_f32_16x16x32_bf16 v[34:37], v[170:173], v[186:189], v[34:37]
	v_mfma_f32_16x16x32_bf16 v[22:25], v[162:165], v[194:197], v[22:25]
	v_mfma_f32_16x16x32_bf16 v[18:21], v[170:173], v[194:197], v[18:21]
	v_mfma_f32_16x16x32_bf16 v[6:9], v[162:165], v[202:205], v[6:9]
	v_mfma_f32_16x16x32_bf16 v[2:5], v[170:173], v[202:205], v[2:5]
	v_mfma_f32_16x16x32_bf16 v[54:57], v[166:169], v[182:185], v[54:57]
	v_mfma_f32_16x16x32_bf16 v[50:53], v[174:177], v[182:185], v[50:53]
	v_mfma_f32_16x16x32_bf16 v[38:41], v[166:169], v[190:193], v[38:41]
	v_mfma_f32_16x16x32_bf16 v[34:37], v[174:177], v[190:193], v[34:37]
	v_mfma_f32_16x16x32_bf16 v[22:25], v[166:169], v[198:201], v[22:25]
	v_mfma_f32_16x16x32_bf16 v[18:21], v[174:177], v[198:201], v[18:21]
	v_mfma_f32_16x16x32_bf16 v[6:9], v[166:169], v[222:225], v[6:9]
	v_mfma_f32_16x16x32_bf16 v[2:5], v[174:177], v[222:225], v[2:5]
	s_barrier
	s_setprio 0
	s_waitcnt vmcnt(8)
	s_add_i32 s48, s48, 2
	s_add_u32 s46, s46, 0x100
	s_addc_u32 s47, s47, 0
	s_cmp_gt_u32 s48, 13
	s_mov_b64 s[4:5], s[2:3]
	s_cbranch_scc0 .LBB0_650
	s_and_b64 vcc, exec, s[12:13]
	s_cbranch_vccz .LBB0_653
	s_barrier

.LBB0_783:
	s_add_u32 s2, s4, 0xfffc0080
	s_addc_u32 s3, s5, -1
	s_add_i32 s48, 0, 0x10000
	s_cmp_eq_u32 s47, 12
	s_cselect_b32 s27, s17, s3
	s_cselect_b32 s26, s25, s2
	s_cselect_b32 s3, s15, s46
	s_cselect_b32 s2, s41, s42
	s_add_i32 s50, 0, 0x14000
	v_add_u32_e32 v154, s48, v140
	v_add_u32_e32 v170, s50, v140
	ds_read_b128 v[142:145], v154
	ds_read_b128 v[146:149], v154 offset:1024
	ds_read_b128 v[150:153], v154 offset:2048
	ds_read_b128 v[154:157], v154 offset:3072
	ds_read_b128 v[158:161], v170
	ds_read_b128 v[162:165], v170 offset:1024
	ds_read_b128 v[166:169], v170 offset:2048
	ds_read_b128 v[170:173], v170 offset:3072
	v_lshl_add_u64 v[206:207], s[4:5], 0, v[136:137]
	s_add_i32 m0, s23, 0xc000
	ds_read_b128 v[174:177], v141
	ds_read_b128 v[178:181], v141 offset:1024
	ds_read_b128 v[182:185], v141 offset:2048
	ds_read_b128 v[186:189], v141 offset:3072
	ds_read_b128 v[190:193], v141 offset:4096
	ds_read_b128 v[194:197], v141 offset:5120
	ds_read_b128 v[198:201], v141 offset:6144
	ds_read_b128 v[202:205], v141 offset:7168
	global_load_lds_dwordx4 v[206:207], off
	v_lshl_add_u64 v[206:207], s[4:5], 0, v[138:139]
	s_add_i32 m0, s23, 0xe000
	s_nop 0
	global_load_lds_dwordx4 v[206:207], off
	s_and_b64 s[98:99], exec, s[12:13]
	s_cbranch_scc1 .Lvd_8
	s_waitcnt vmcnt(8)
.Lvd_8:
	s_waitcnt lgkmcnt(0)
	s_setprio 1
	s_barrier
	v_mfma_f32_16x16x32_bf16 v[122:125], v[142:145], v[174:177], v[122:125]
	v_mfma_f32_16x16x32_bf16 v[114:117], v[150:153], v[174:177], v[114:117]
	v_mfma_f32_16x16x32_bf16 v[106:109], v[142:145], v[182:185], v[106:109]
	v_mfma_f32_16x16x32_bf16 v[98:101], v[150:153], v[182:185], v[98:101]
	v_mfma_f32_16x16x32_bf16 v[90:93], v[142:145], v[190:193], v[90:93]
	v_mfma_f32_16x16x32_bf16 v[82:85], v[150:153], v[190:193], v[82:85]
	v_mfma_f32_16x16x32_bf16 v[74:77], v[142:145], v[198:201], v[74:77]
	v_mfma_f32_16x16x32_bf16 v[66:69], v[150:153], v[198:201], v[66:69]
	v_mfma_f32_16x16x32_bf16 v[122:125], v[146:149], v[178:181], v[122:125]
	v_mfma_f32_16x16x32_bf16 v[114:117], v[154:157], v[178:181], v[114:117]
	v_mfma_f32_16x16x32_bf16 v[106:109], v[146:149], v[186:189], v[106:109]
	v_mfma_f32_16x16x32_bf16 v[98:101], v[154:157], v[186:189], v[98:101]
	v_mfma_f32_16x16x32_bf16 v[90:93], v[146:149], v[194:197], v[90:93]
	v_mfma_f32_16x16x32_bf16 v[82:85], v[154:157], v[194:197], v[82:85]
	v_mfma_f32_16x16x32_bf16 v[74:77], v[146:149], v[202:205], v[74:77]
	v_mfma_f32_16x16x32_bf16 v[66:69], v[154:157], v[202:205], v[66:69]
	v_mfma_f32_16x16x32_bf16 v[126:129], v[158:161], v[174:177], v[126:129]
	v_mfma_f32_16x16x32_bf16 v[118:121], v[166:169], v[174:177], v[118:121]
	v_mfma_f32_16x16x32_bf16 v[110:113], v[158:161], v[182:185], v[110:113]
	v_mfma_f32_16x16x32_bf16 v[102:105], v[166:169], v[182:185], v[102:105]
	v_mfma_f32_16x16x32_bf16 v[94:97], v[158:161], v[190:193], v[94:97]
	v_mfma_f32_16x16x32_bf16 v[86:89], v[166:169], v[190:193], v[86:89]
	v_mfma_f32_16x16x32_bf16 v[78:81], v[158:161], v[198:201], v[78:81]
	v_mfma_f32_16x16x32_bf16 v[70:73], v[166:169], v[198:201], v[70:73]
	v_mfma_f32_16x16x32_bf16 v[126:129], v[162:165], v[178:181], v[126:129]
	v_mfma_f32_16x16x32_bf16 v[118:121], v[170:173], v[178:181], v[118:121]
	v_mfma_f32_16x16x32_bf16 v[110:113], v[162:165], v[186:189], v[110:113]
	v_mfma_f32_16x16x32_bf16 v[102:105], v[170:173], v[186:189], v[102:105]
	v_mfma_f32_16x16x32_bf16 v[94:97], v[162:165], v[194:197], v[94:97]
	v_mfma_f32_16x16x32_bf16 v[86:89], v[170:173], v[194:197], v[86:89]
	v_mfma_f32_16x16x32_bf16 v[78:81], v[162:165], v[202:205], v[78:81]
	v_mfma_f32_16x16x32_bf16 v[70:73], v[170:173], v[202:205], v[70:73]
	s_barrier
	s_setprio 0
	s_waitcnt vmcnt(8)
	s_add_i32 s48, s48, s28
	v_lshl_add_u64 v[206:207], s[2:3], 0, v[132:133]
	s_mov_b32 m0, s48
	ds_read_b128 v[174:177], v141 offset:16384
	ds_read_b128 v[178:181], v141 offset:17408
	ds_read_b128 v[182:185], v141 offset:18432
	ds_read_b128 v[186:189], v141 offset:19456
	ds_read_b128 v[190:193], v141 offset:20480
	ds_read_b128 v[194:197], v141 offset:21504
	ds_read_b128 v[198:201], v141 offset:22528
	ds_read_b128 v[202:205], v141 offset:23552
	global_load_lds_dwordx4 v[206:207], off
	s_add_i32 m0, s48, 0x2000
	s_add_u32 s48, s2, 0x40000
	v_lshl_add_u64 v[218:219], s[2:3], 0, v[130:131]
	s_addc_u32 s49, s3, 0
	s_add_i32 s50, s50, s28
	global_load_lds_dwordx4 v[218:219], off
	v_lshl_add_u64 v[222:223], s[48:49], 0, v[132:133]
	s_mov_b32 m0, s50
	v_lshl_add_u64 v[224:225], s[26:27], 0, v[130:131]
	global_load_lds_dwordx4 v[222:223], off
	v_lshl_add_u64 v[222:223], s[48:49], 0, v[130:131]
	s_add_i32 m0, s50, 0x2000
	s_nop 0
	global_load_lds_dwordx4 v[222:223], off
	v_lshl_add_u64 v[222:223], s[26:27], 0, v[132:133]
	s_mov_b32 m0, s23
	s_nop 0
	global_load_lds_dwordx4 v[222:223], off
	s_mov_b32 m0, s31
	s_nop 0
	global_load_lds_dwordx4 v[224:225], off
	s_and_b64 s[98:99], exec, s[12:13]
	s_cbranch_scc1 .Lvd_9
	s_waitcnt vmcnt(8)
.Lvd_9:
	s_waitcnt lgkmcnt(0)
	s_setprio 1
	s_barrier
	v_mfma_f32_16x16x32_bf16 v[58:61], v[142:145], v[174:177], v[58:61]
	v_mfma_f32_16x16x32_bf16 v[50:53], v[150:153], v[174:177], v[50:53]
	v_mfma_f32_16x16x32_bf16 v[42:45], v[142:145], v[182:185], v[42:45]
	v_mfma_f32_16x16x32_bf16 v[34:37], v[150:153], v[182:185], v[34:37]
	v_mfma_f32_16x16x32_bf16 v[26:29], v[142:145], v[190:193], v[26:29]
	v_mfma_f32_16x16x32_bf16 v[18:21], v[150:153], v[190:193], v[18:21]
	v_mfma_f32_16x16x32_bf16 v[10:13], v[142:145], v[198:201], v[10:13]
	v_mfma_f32_16x16x32_bf16 v[2:5], v[150:153], v[198:201], v[2:5]
	v_mfma_f32_16x16x32_bf16 v[58:61], v[146:149], v[178:181], v[58:61]
	v_mfma_f32_16x16x32_bf16 v[50:53], v[154:157], v[178:181], v[50:53]
	v_mfma_f32_16x16x32_bf16 v[42:45], v[146:149], v[186:189], v[42:45]
	v_mfma_f32_16x16x32_bf16 v[34:37], v[154:157], v[186:189], v[34:37]
	v_mfma_f32_16x16x32_bf16 v[26:29], v[146:149], v[194:197], v[26:29]
	v_mfma_f32_16x16x32_bf16 v[18:21], v[154:157], v[194:197], v[18:21]
	v_mfma_f32_16x16x32_bf16 v[10:13], v[146:149], v[202:205], v[10:13]
	v_mfma_f32_16x16x32_bf16 v[2:5], v[154:157], v[202:205], v[2:5]
	v_mfma_f32_16x16x32_bf16 v[62:65], v[158:161], v[174:177], v[62:65]
	v_mfma_f32_16x16x32_bf16 v[54:57], v[166:169], v[174:177], v[54:57]
	v_mfma_f32_16x16x32_bf16 v[46:49], v[158:161], v[182:185], v[46:49]
	v_mfma_f32_16x16x32_bf16 v[38:41], v[166:169], v[182:185], v[38:41]
	v_mfma_f32_16x16x32_bf16 v[30:33], v[158:161], v[190:193], v[30:33]
	v_mfma_f32_16x16x32_bf16 v[22:25], v[166:169], v[190:193], v[22:25]
	v_mfma_f32_16x16x32_bf16 v[14:17], v[158:161], v[198:201], v[14:17]
	v_mfma_f32_16x16x32_bf16 v[6:9], v[166:169], v[198:201], v[6:9]
	v_mfma_f32_16x16x32_bf16 v[62:65], v[162:165], v[178:181], v[62:65]
	v_mfma_f32_16x16x32_bf16 v[54:57], v[170:173], v[178:181], v[54:57]
	v_mfma_f32_16x16x32_bf16 v[46:49], v[162:165], v[186:189], v[46:49]
	v_mfma_f32_16x16x32_bf16 v[38:41], v[170:173], v[186:189], v[38:41]
	v_mfma_f32_16x16x32_bf16 v[30:33], v[162:165], v[194:197], v[30:33]
	v_mfma_f32_16x16x32_bf16 v[22:25], v[170:173], v[194:197], v[22:25]
	v_mfma_f32_16x16x32_bf16 v[14:17], v[162:165], v[202:205], v[14:17]
	v_mfma_f32_16x16x32_bf16 v[6:9], v[170:173], v[202:205], v[6:9]
	s_barrier
	s_setprio 0
	s_waitcnt vmcnt(8)
	s_add_i32 s48, 0, 0x18000
	s_add_i32 s49, 0, 0x1c000
	v_add_u32_e32 v154, s48, v140
	v_add_u32_e32 v170, s49, v140
	ds_read_b128 v[142:145], v154
	ds_read_b128 v[146:149], v154 offset:1024
	ds_read_b128 v[150:153], v154 offset:2048
	ds_read_b128 v[154:157], v154 offset:3072
	ds_read_b128 v[158:161], v170
	ds_read_b128 v[162:165], v170 offset:1024
	ds_read_b128 v[166:169], v170 offset:2048
	ds_read_b128 v[170:173], v170 offset:3072
	s_add_u32 s26, s26, 0x40000
	s_addc_u32 s27, s27, 0
	s_mov_b32 m0, s33
	v_lshl_add_u64 v[226:227], s[26:27], 0, v[132:133]
	ds_read_b128 v[174:177], v141 offset:32768
	ds_read_b128 v[178:181], v141 offset:33792
	ds_read_b128 v[182:185], v141 offset:34816
	ds_read_b128 v[186:189], v141 offset:35840
	ds_read_b128 v[190:193], v141 offset:36864
	ds_read_b128 v[194:197], v141 offset:37888
	ds_read_b128 v[198:201], v141 offset:38912
	ds_read_b128 v[202:205], v141 offset:39936
	global_load_lds_dwordx4 v[226:227], off
	v_lshl_add_u64 v[226:227], s[26:27], 0, v[130:131]
	s_mov_b32 m0, s34
	s_nop 0
	global_load_lds_dwordx4 v[226:227], off
	s_and_b64 s[98:99], exec, s[12:13]
	s_cbranch_scc1 .Lvd_10
	s_waitcnt vmcnt(8)
.Lvd_10:
	s_waitcnt lgkmcnt(0)
	s_setprio 1
	s_barrier
	v_mfma_f32_16x16x32_bf16 v[122:125], v[142:145], v[174:177], v[122:125]
	v_mfma_f32_16x16x32_bf16 v[114:117], v[150:153], v[174:177], v[114:117]
	v_mfma_f32_16x16x32_bf16 v[106:109], v[142:145], v[182:185], v[106:109]
	v_mfma_f32_16x16x32_bf16 v[98:101], v[150:153], v[182:185], v[98:101]
	v_mfma_f32_16x16x32_bf16 v[90:93], v[142:145], v[190:193], v[90:93]
	v_mfma_f32_16x16x32_bf16 v[82:85], v[150:153], v[190:193], v[82:85]
	v_mfma_f32_16x16x32_bf16 v[74:77], v[142:145], v[198:201], v[74:77]
	v_mfma_f32_16x16x32_bf16 v[66:69], v[150:153], v[198:201], v[66:69]
	v_mfma_f32_16x16x32_bf16 v[122:125], v[146:149], v[178:181], v[122:125]
	v_mfma_f32_16x16x32_bf16 v[114:117], v[154:157], v[178:181], v[114:117]
	v_mfma_f32_16x16x32_bf16 v[106:109], v[146:149], v[186:189], v[106:109]
	v_mfma_f32_16x16x32_bf16 v[98:101], v[154:157], v[186:189], v[98:101]
	v_mfma_f32_16x16x32_bf16 v[90:93], v[146:149], v[194:197], v[90:93]
	v_mfma_f32_16x16x32_bf16 v[82:85], v[154:157], v[194:197], v[82:85]
	v_mfma_f32_16x16x32_bf16 v[74:77], v[146:149], v[202:205], v[74:77]
	v_mfma_f32_16x16x32_bf16 v[66:69], v[154:157], v[202:205], v[66:69]
	v_mfma_f32_16x16x32_bf16 v[126:129], v[158:161], v[174:177], v[126:129]
	v_mfma_f32_16x16x32_bf16 v[118:121], v[166:169], v[174:177], v[118:121]
	v_mfma_f32_16x16x32_bf16 v[110:113], v[158:161], v[182:185], v[110:113]
	v_mfma_f32_16x16x32_bf16 v[102:105], v[166:169], v[182:185], v[102:105]
	v_mfma_f32_16x16x32_bf16 v[94:97], v[158:161], v[190:193], v[94:97]
	v_mfma_f32_16x16x32_bf16 v[86:89], v[166:169], v[190:193], v[86:89]
	v_mfma_f32_16x16x32_bf16 v[78:81], v[158:161], v[198:201], v[78:81]
	v_mfma_f32_16x16x32_bf16 v[70:73], v[166:169], v[198:201], v[70:73]
	v_mfma_f32_16x16x32_bf16 v[126:129], v[162:165], v[178:181], v[126:129]
	v_mfma_f32_16x16x32_bf16 v[118:121], v[170:173], v[178:181], v[118:121]
	v_mfma_f32_16x16x32_bf16 v[110:113], v[162:165], v[186:189], v[110:113]
	v_mfma_f32_16x16x32_bf16 v[102:105], v[170:173], v[186:189], v[102:105]
	v_mfma_f32_16x16x32_bf16 v[94:97], v[162:165], v[194:197], v[94:97]
	v_mfma_f32_16x16x32_bf16 v[86:89], v[170:173], v[194:197], v[86:89]
	v_mfma_f32_16x16x32_bf16 v[78:81], v[162:165], v[202:205], v[78:81]
	v_mfma_f32_16x16x32_bf16 v[70:73], v[170:173], v[202:205], v[70:73]
	s_barrier
	s_setprio 0
	s_waitcnt vmcnt(8)
	s_add_i32 s26, s48, s28
	v_lshl_add_u64 v[206:207], v[206:207], 0, s[44:45]
	s_mov_b32 m0, s26
	ds_read_b128 v[174:177], v141 offset:49152
	ds_read_b128 v[178:181], v141 offset:50176
	ds_read_b128 v[182:185], v141 offset:51200
	ds_read_b128 v[186:189], v141 offset:52224
	ds_read_b128 v[190:193], v141 offset:53248
	ds_read_b128 v[194:197], v141 offset:54272
	ds_read_b128 v[198:201], v141 offset:55296
	ds_read_b128 v[202:205], v141 offset:56320
	global_load_lds_dwordx4 v[206:207], off
	s_add_i32 m0, s26, 0x2000
	s_add_u32 s2, s2, 0x40080
	v_lshl_add_u64 v[206:207], v[218:219], 0, s[44:45]
	s_addc_u32 s3, s3, 0
	s_add_i32 s26, s49, s28
	global_load_lds_dwordx4 v[206:207], off
	v_lshl_add_u64 v[206:207], s[2:3], 0, v[132:133]
	s_mov_b32 m0, s26
	s_nop 0
	global_load_lds_dwordx4 v[206:207], off
	v_lshl_add_u64 v[206:207], s[2:3], 0, v[130:131]
	s_add_i32 m0, s26, 0x2000
	s_nop 0
	global_load_lds_dwordx4 v[206:207], off
	v_lshl_add_u64 v[206:207], v[222:223], 0, s[44:45]
	s_mov_b32 m0, s35
	s_nop 0
	global_load_lds_dwordx4 v[206:207], off
	v_lshl_add_u64 v[206:207], v[224:225], 0, s[44:45]
	s_mov_b32 m0, s36
	s_nop 0
	global_load_lds_dwordx4 v[206:207], off
	s_and_b64 s[98:99], exec, s[12:13]
	s_cbranch_scc1 .Lvd_11
	s_waitcnt vmcnt(8)
.Lvd_11:
	s_waitcnt lgkmcnt(0)
	s_setprio 1
	s_barrier
	v_mfma_f32_16x16x32_bf16 v[58:61], v[142:145], v[174:177], v[58:61]
	v_mfma_f32_16x16x32_bf16 v[50:53], v[150:153], v[174:177], v[50:53]
	v_mfma_f32_16x16x32_bf16 v[42:45], v[142:145], v[182:185], v[42:45]
	v_mfma_f32_16x16x32_bf16 v[34:37], v[150:153], v[182:185], v[34:37]
	v_mfma_f32_16x16x32_bf16 v[26:29], v[142:145], v[190:193], v[26:29]
	v_mfma_f32_16x16x32_bf16 v[18:21], v[150:153], v[190:193], v[18:21]
	v_mfma_f32_16x16x32_bf16 v[10:13], v[142:145], v[198:201], v[10:13]
	v_mfma_f32_16x16x32_bf16 v[2:5], v[150:153], v[198:201], v[2:5]
	v_mfma_f32_16x16x32_bf16 v[58:61], v[146:149], v[178:181], v[58:61]
	v_mfma_f32_16x16x32_bf16 v[50:53], v[154:157], v[178:181], v[50:53]
	v_mfma_f32_16x16x32_bf16 v[42:45], v[146:149], v[186:189], v[42:45]
	v_mfma_f32_16x16x32_bf16 v[34:37], v[154:157], v[186:189], v[34:37]
	v_mfma_f32_16x16x32_bf16 v[26:29], v[146:149], v[194:197], v[26:29]
	v_mfma_f32_16x16x32_bf16 v[18:21], v[154:157], v[194:197], v[18:21]
	v_mfma_f32_16x16x32_bf16 v[10:13], v[146:149], v[202:205], v[10:13]
	v_mfma_f32_16x16x32_bf16 v[2:5], v[154:157], v[202:205], v[2:5]
	v_mfma_f32_16x16x32_bf16 v[62:65], v[158:161], v[174:177], v[62:65]
	v_mfma_f32_16x16x32_bf16 v[54:57], v[166:169], v[174:177], v[54:57]
	v_mfma_f32_16x16x32_bf16 v[46:49], v[158:161], v[182:185], v[46:49]
	v_mfma_f32_16x16x32_bf16 v[38:41], v[166:169], v[182:185], v[38:41]
	v_mfma_f32_16x16x32_bf16 v[30:33], v[158:161], v[190:193], v[30:33]
	v_mfma_f32_16x16x32_bf16 v[22:25], v[166:169], v[190:193], v[22:25]
	v_mfma_f32_16x16x32_bf16 v[14:17], v[158:161], v[198:201], v[14:17]
	v_mfma_f32_16x16x32_bf16 v[6:9], v[166:169], v[198:201], v[6:9]
	v_mfma_f32_16x16x32_bf16 v[62:65], v[162:165], v[178:181], v[62:65]
	v_mfma_f32_16x16x32_bf16 v[54:57], v[170:173], v[178:181], v[54:57]
	v_mfma_f32_16x16x32_bf16 v[46:49], v[162:165], v[186:189], v[46:49]
	v_mfma_f32_16x16x32_bf16 v[38:41], v[170:173], v[186:189], v[38:41]
	v_mfma_f32_16x16x32_bf16 v[30:33], v[162:165], v[194:197], v[30:33]
	v_mfma_f32_16x16x32_bf16 v[22:25], v[170:173], v[194:197], v[22:25]
	v_mfma_f32_16x16x32_bf16 v[14:17], v[162:165], v[202:205], v[14:17]
	v_mfma_f32_16x16x32_bf16 v[6:9], v[170:173], v[202:205], v[6:9]
	s_barrier
	s_setprio 0
	s_waitcnt vmcnt(8)
	s_add_i32 s47, s47, 2
	s_add_u32 s4, s4, 0x100
	s_addc_u32 s5, s5, 0
	s_add_u32 s42, s42, 0x100
	s_addc_u32 s46, s46, 0
	s_cmp_gt_u32 s47, 13
	s_cbranch_scc0 .LBB0_783
	s_and_b64 vcc, exec, s[12:13]
	s_cbranch_vccz .LBB0_786
	s_barrier

.LBB0_849:
	s_add_u32 s2, s18, 0x100
	s_addc_u32 s3, s19, 0
	s_add_i32 s47, 0, 0x10000
	s_cmp_eq_u32 s46, 40
	s_cselect_b32 s23, s9, s3
	s_cselect_b32 s22, s8, s2
	v_add_u32_e32 v0, s47, v135
	s_cselect_b32 s21, s15, s42
	s_cselect_b32 s20, s14, s17
	s_add_i32 s48, 0, 0x14000
	ds_read_b128 v[146:149], v0
	ds_read_b128 v[150:153], v0 offset:1024
	ds_read_b128 v[154:157], v0 offset:2048
	ds_read_b128 v[158:161], v0 offset:3072
	v_add_u32_e32 v0, s48, v135
	ds_read_b128 v[162:165], v0
	ds_read_b128 v[166:169], v0 offset:1024
	ds_read_b128 v[170:173], v0 offset:2048
	ds_read_b128 v[174:177], v0 offset:3072
	v_lshl_add_u64 v[142:143], s[18:19], 0, v[138:139]
	s_add_i32 m0, s25, 0xc000
	ds_read_b128 v[178:181], v144
	ds_read_b128 v[182:185], v144 offset:1024
	ds_read_b128 v[186:189], v144 offset:2048
	ds_read_b128 v[190:193], v144 offset:3072
	ds_read_b128 v[194:197], v144 offset:4096
	ds_read_b128 v[198:201], v144 offset:5120
	ds_read_b128 v[202:205], v144 offset:6144
	ds_read_b128 v[222:225], v144 offset:7168
	global_load_lds_dwordx4 v[142:143], off
	v_lshl_add_u64 v[142:143], s[18:19], 0, v[140:141]
	s_add_i32 m0, s25, 0xe000
	s_nop 0
	global_load_lds_dwordx4 v[142:143], off
	s_and_b64 s[98:99], exec, s[12:13]
	s_cbranch_scc1 .Lvd_12
	s_waitcnt vmcnt(8)
.Lvd_12:
	s_waitcnt lgkmcnt(0)
	s_setprio 1
	s_barrier
	v_mfma_f32_16x16x32_bf16 v[126:129], v[146:149], v[178:181], v[126:129]
	v_mfma_f32_16x16x32_bf16 v[122:125], v[154:157], v[178:181], v[122:125]
	v_mfma_f32_16x16x32_bf16 v[110:113], v[146:149], v[186:189], v[110:113]
	v_mfma_f32_16x16x32_bf16 v[106:109], v[154:157], v[186:189], v[106:109]
	v_mfma_f32_16x16x32_bf16 v[94:97], v[146:149], v[194:197], v[94:97]
	v_mfma_f32_16x16x32_bf16 v[90:93], v[154:157], v[194:197], v[90:93]
	v_mfma_f32_16x16x32_bf16 v[78:81], v[146:149], v[202:205], v[78:81]
	v_mfma_f32_16x16x32_bf16 v[74:77], v[154:157], v[202:205], v[74:77]
	v_mfma_f32_16x16x32_bf16 v[126:129], v[150:153], v[182:185], v[126:129]
	v_mfma_f32_16x16x32_bf16 v[122:125], v[158:161], v[182:185], v[122:125]
	v_mfma_f32_16x16x32_bf16 v[110:113], v[150:153], v[190:193], v[110:113]
	v_mfma_f32_16x16x32_bf16 v[106:109], v[158:161], v[190:193], v[106:109]
	v_mfma_f32_16x16x32_bf16 v[94:97], v[150:153], v[198:201], v[94:97]
	v_mfma_f32_16x16x32_bf16 v[90:93], v[158:161], v[198:201], v[90:93]
	v_mfma_f32_16x16x32_bf16 v[78:81], v[150:153], v[222:225], v[78:81]
	v_mfma_f32_16x16x32_bf16 v[74:77], v[158:161], v[222:225], v[74:77]
	v_mfma_f32_16x16x32_bf16 v[118:121], v[162:165], v[178:181], v[118:121]
	v_mfma_f32_16x16x32_bf16 v[114:117], v[170:173], v[178:181], v[114:117]
	v_mfma_f32_16x16x32_bf16 v[102:105], v[162:165], v[186:189], v[102:105]
	v_mfma_f32_16x16x32_bf16 v[98:101], v[170:173], v[186:189], v[98:101]
	v_mfma_f32_16x16x32_bf16 v[86:89], v[162:165], v[194:197], v[86:89]
	v_mfma_f32_16x16x32_bf16 v[82:85], v[170:173], v[194:197], v[82:85]
	v_mfma_f32_16x16x32_bf16 v[70:73], v[162:165], v[202:205], v[70:73]
	v_mfma_f32_16x16x32_bf16 v[66:69], v[170:173], v[202:205], v[66:69]
	v_mfma_f32_16x16x32_bf16 v[118:121], v[166:169], v[182:185], v[118:121]
	v_mfma_f32_16x16x32_bf16 v[114:117], v[174:177], v[182:185], v[114:117]
	v_mfma_f32_16x16x32_bf16 v[102:105], v[166:169], v[190:193], v[102:105]
	v_mfma_f32_16x16x32_bf16 v[98:101], v[174:177], v[190:193], v[98:101]
	v_mfma_f32_16x16x32_bf16 v[86:89], v[166:169], v[198:201], v[86:89]
	v_mfma_f32_16x16x32_bf16 v[82:85], v[174:177], v[198:201], v[82:85]
	v_mfma_f32_16x16x32_bf16 v[70:73], v[166:169], v[222:225], v[70:73]
	v_mfma_f32_16x16x32_bf16 v[66:69], v[174:177], v[222:225], v[66:69]
	s_barrier
	s_setprio 0
	s_waitcnt vmcnt(8)
	s_add_i32 s18, s47, s24
	v_lshl_add_u64 v[142:143], s[20:21], 0, v[130:131]
	s_mov_b32 m0, s18
	ds_read_b128 v[178:181], v144 offset:16384
	ds_read_b128 v[182:185], v144 offset:17408
	ds_read_b128 v[186:189], v144 offset:18432
	ds_read_b128 v[190:193], v144 offset:19456
	ds_read_b128 v[194:197], v144 offset:20480
	ds_read_b128 v[198:201], v144 offset:21504
	ds_read_b128 v[202:205], v144 offset:22528
	ds_read_b128 v[222:225], v144 offset:23552
	global_load_lds_dwordx4 v[142:143], off
	s_add_i32 m0, s18, 0x2000
	s_add_u32 s18, s20, 0xb0000
	v_lshl_add_u64 v[206:207], s[20:21], 0, v[132:133]
	s_addc_u32 s19, s21, 0
	s_add_i32 s47, s48, s24
	global_load_lds_dwordx4 v[206:207], off
	v_lshl_add_u64 v[218:219], s[18:19], 0, v[130:131]
	s_mov_b32 m0, s47
	v_lshl_add_u64 v[226:227], s[22:23], 0, v[132:133]
	global_load_lds_dwordx4 v[218:219], off
	v_lshl_add_u64 v[218:219], s[18:19], 0, v[132:133]
	s_add_i32 m0, s47, 0x2000
	s_nop 0
	global_load_lds_dwordx4 v[218:219], off
	v_lshl_add_u64 v[218:219], s[22:23], 0, v[130:131]
	s_mov_b32 m0, s25
	s_nop 0
	global_load_lds_dwordx4 v[218:219], off
	s_mov_b32 m0, s26
	s_nop 0
	global_load_lds_dwordx4 v[226:227], off
	s_and_b64 s[98:99], exec, s[12:13]
	s_cbranch_scc1 .Lvd_13
	s_waitcnt vmcnt(8)
.Lvd_13:
	s_waitcnt lgkmcnt(0)
	s_setprio 1
	s_barrier
	v_mfma_f32_16x16x32_bf16 v[62:65], v[146:149], v[178:181], v[62:65]
	v_mfma_f32_16x16x32_bf16 v[58:61], v[154:157], v[178:181], v[58:61]
	v_mfma_f32_16x16x32_bf16 v[46:49], v[146:149], v[186:189], v[46:49]
	v_mfma_f32_16x16x32_bf16 v[42:45], v[154:157], v[186:189], v[42:45]
	v_mfma_f32_16x16x32_bf16 v[30:33], v[146:149], v[194:197], v[30:33]
	v_mfma_f32_16x16x32_bf16 v[26:29], v[154:157], v[194:197], v[26:29]
	v_mfma_f32_16x16x32_bf16 v[14:17], v[146:149], v[202:205], v[14:17]
	v_mfma_f32_16x16x32_bf16 v[10:13], v[154:157], v[202:205], v[10:13]
	v_mfma_f32_16x16x32_bf16 v[62:65], v[150:153], v[182:185], v[62:65]
	v_mfma_f32_16x16x32_bf16 v[58:61], v[158:161], v[182:185], v[58:61]
	v_mfma_f32_16x16x32_bf16 v[46:49], v[150:153], v[190:193], v[46:49]
	v_mfma_f32_16x16x32_bf16 v[42:45], v[158:161], v[190:193], v[42:45]
	v_mfma_f32_16x16x32_bf16 v[30:33], v[150:153], v[198:201], v[30:33]
	v_mfma_f32_16x16x32_bf16 v[26:29], v[158:161], v[198:201], v[26:29]
	v_mfma_f32_16x16x32_bf16 v[14:17], v[150:153], v[222:225], v[14:17]
	v_mfma_f32_16x16x32_bf16 v[10:13], v[158:161], v[222:225], v[10:13]
	v_mfma_f32_16x16x32_bf16 v[54:57], v[162:165], v[178:181], v[54:57]
	v_mfma_f32_16x16x32_bf16 v[50:53], v[170:173], v[178:181], v[50:53]
	v_mfma_f32_16x16x32_bf16 v[38:41], v[162:165], v[186:189], v[38:41]
	v_mfma_f32_16x16x32_bf16 v[34:37], v[170:173], v[186:189], v[34:37]
	v_mfma_f32_16x16x32_bf16 v[22:25], v[162:165], v[194:197], v[22:25]
	v_mfma_f32_16x16x32_bf16 v[18:21], v[170:173], v[194:197], v[18:21]
	v_mfma_f32_16x16x32_bf16 v[6:9], v[162:165], v[202:205], v[6:9]
	v_mfma_f32_16x16x32_bf16 v[2:5], v[170:173], v[202:205], v[2:5]
	v_mfma_f32_16x16x32_bf16 v[54:57], v[166:169], v[182:185], v[54:57]
	v_mfma_f32_16x16x32_bf16 v[50:53], v[174:177], v[182:185], v[50:53]
	v_mfma_f32_16x16x32_bf16 v[38:41], v[166:169], v[190:193], v[38:41]
	v_mfma_f32_16x16x32_bf16 v[34:37], v[174:177], v[190:193], v[34:37]
	v_mfma_f32_16x16x32_bf16 v[22:25], v[166:169], v[198:201], v[22:25]
	v_mfma_f32_16x16x32_bf16 v[18:21], v[174:177], v[198:201], v[18:21]
	v_mfma_f32_16x16x32_bf16 v[6:9], v[166:169], v[222:225], v[6:9]
	v_mfma_f32_16x16x32_bf16 v[2:5], v[174:177], v[222:225], v[2:5]
	s_barrier
	s_setprio 0
	s_waitcnt vmcnt(8)
	s_add_i32 s47, 0, 0x18000
	v_add_u32_e32 v0, s47, v135
	s_add_i32 s48, 0, 0x1c000
	ds_read_b128 v[146:149], v0
	ds_read_b128 v[150:153], v0 offset:1024
	ds_read_b128 v[154:157], v0 offset:2048
	ds_read_b128 v[158:161], v0 offset:3072
	v_add_u32_e32 v0, s48, v135
	ds_read_b128 v[162:165], v0
	ds_read_b128 v[166:169], v0 offset:1024
	ds_read_b128 v[170:173], v0 offset:2048
	ds_read_b128 v[174:177], v0 offset:3072
	s_add_u32 s18, s22, 0xb0000
	s_addc_u32 s19, s23, 0
	s_mov_b32 m0, s27
	v_lshl_add_u64 v[228:229], s[18:19], 0, v[130:131]
	ds_read_b128 v[178:181], v144 offset:32768
	ds_read_b128 v[182:185], v144 offset:33792
	ds_read_b128 v[186:189], v144 offset:34816
	ds_read_b128 v[190:193], v144 offset:35840
	ds_read_b128 v[194:197], v144 offset:36864
	ds_read_b128 v[198:201], v144 offset:37888
	ds_read_b128 v[202:205], v144 offset:38912
	ds_read_b128 v[222:225], v144 offset:39936
	global_load_lds_dwordx4 v[228:229], off
	v_lshl_add_u64 v[228:229], s[18:19], 0, v[132:133]
	s_mov_b32 m0, s28
	s_nop 0
	global_load_lds_dwordx4 v[228:229], off
	s_and_b64 s[98:99], exec, s[12:13]
	s_cbranch_scc1 .Lvd_14
	s_waitcnt vmcnt(8)
.Lvd_14:
	s_waitcnt lgkmcnt(0)
	s_setprio 1
	s_barrier
	v_mfma_f32_16x16x32_bf16 v[126:129], v[146:149], v[178:181], v[126:129]
	v_mfma_f32_16x16x32_bf16 v[122:125], v[154:157], v[178:181], v[122:125]
	v_mfma_f32_16x16x32_bf16 v[110:113], v[146:149], v[186:189], v[110:113]
	v_mfma_f32_16x16x32_bf16 v[106:109], v[154:157], v[186:189], v[106:109]
	v_mfma_f32_16x16x32_bf16 v[94:97], v[146:149], v[194:197], v[94:97]
	v_mfma_f32_16x16x32_bf16 v[90:93], v[154:157], v[194:197], v[90:93]
	v_mfma_f32_16x16x32_bf16 v[78:81], v[146:149], v[202:205], v[78:81]
	v_mfma_f32_16x16x32_bf16 v[74:77], v[154:157], v[202:205], v[74:77]
	v_mfma_f32_16x16x32_bf16 v[126:129], v[150:153], v[182:185], v[126:129]
	v_mfma_f32_16x16x32_bf16 v[122:125], v[158:161], v[182:185], v[122:125]
	v_mfma_f32_16x16x32_bf16 v[110:113], v[150:153], v[190:193], v[110:113]
	v_mfma_f32_16x16x32_bf16 v[106:109], v[158:161], v[190:193], v[106:109]
	v_mfma_f32_16x16x32_bf16 v[94:97], v[150:153], v[198:201], v[94:97]
	v_mfma_f32_16x16x32_bf16 v[90:93], v[158:161], v[198:201], v[90:93]
	v_mfma_f32_16x16x32_bf16 v[78:81], v[150:153], v[222:225], v[78:81]
	v_mfma_f32_16x16x32_bf16 v[74:77], v[158:161], v[222:225], v[74:77]
	v_mfma_f32_16x16x32_bf16 v[118:121], v[162:165], v[178:181], v[118:121]
	v_mfma_f32_16x16x32_bf16 v[114:117], v[170:173], v[178:181], v[114:117]
	v_mfma_f32_16x16x32_bf16 v[102:105], v[162:165], v[186:189], v[102:105]
	v_mfma_f32_16x16x32_bf16 v[98:101], v[170:173], v[186:189], v[98:101]
	v_mfma_f32_16x16x32_bf16 v[86:89], v[162:165], v[194:197], v[86:89]
	v_mfma_f32_16x16x32_bf16 v[82:85], v[170:173], v[194:197], v[82:85]
	v_mfma_f32_16x16x32_bf16 v[70:73], v[162:165], v[202:205], v[70:73]
	v_mfma_f32_16x16x32_bf16 v[66:69], v[170:173], v[202:205], v[66:69]
	v_mfma_f32_16x16x32_bf16 v[118:121], v[166:169], v[182:185], v[118:121]
	v_mfma_f32_16x16x32_bf16 v[114:117], v[174:177], v[182:185], v[114:117]
	v_mfma_f32_16x16x32_bf16 v[102:105], v[166:169], v[190:193], v[102:105]
	v_mfma_f32_16x16x32_bf16 v[98:101], v[174:177], v[190:193], v[98:101]
	v_mfma_f32_16x16x32_bf16 v[86:89], v[166:169], v[198:201], v[86:89]
	v_mfma_f32_16x16x32_bf16 v[82:85], v[174:177], v[198:201], v[82:85]
	v_mfma_f32_16x16x32_bf16 v[70:73], v[166:169], v[222:225], v[70:73]
	v_mfma_f32_16x16x32_bf16 v[66:69], v[174:177], v[222:225], v[66:69]
	s_barrier
	s_setprio 0
	s_waitcnt vmcnt(8)
	s_add_i32 s18, s47, s24
	v_lshl_add_u64 v[142:143], v[142:143], 0, s[44:45]
	s_mov_b32 m0, s18
	ds_read_b128 v[178:181], v144 offset:49152
	ds_read_b128 v[182:185], v144 offset:50176
	ds_read_b128 v[186:189], v144 offset:51200
	ds_read_b128 v[190:193], v144 offset:52224
	ds_read_b128 v[194:197], v144 offset:53248
	ds_read_b128 v[198:201], v144 offset:54272
	ds_read_b128 v[202:205], v144 offset:55296
	ds_read_b128 v[222:225], v144 offset:56320
	global_load_lds_dwordx4 v[142:143], off
	s_add_i32 m0, s18, 0x2000
	s_add_u32 s18, s20, 0xb0080
	v_lshl_add_u64 v[142:143], v[206:207], 0, s[44:45]
	s_addc_u32 s19, s21, 0
	s_add_i32 s20, s48, s24
	global_load_lds_dwordx4 v[142:143], off
	v_lshl_add_u64 v[142:143], s[18:19], 0, v[130:131]
	s_mov_b32 m0, s20
	s_nop 0
	global_load_lds_dwordx4 v[142:143], off
	v_lshl_add_u64 v[142:143], s[18:19], 0, v[132:133]
	s_add_i32 m0, s20, 0x2000
	s_nop 0
	global_load_lds_dwordx4 v[142:143], off
	v_lshl_add_u64 v[142:143], v[218:219], 0, s[44:45]
	s_mov_b32 m0, s31
	s_nop 0
	global_load_lds_dwordx4 v[142:143], off
	v_lshl_add_u64 v[142:143], v[226:227], 0, s[44:45]
	s_mov_b32 m0, s33
	s_nop 0
	global_load_lds_dwordx4 v[142:143], off
	s_and_b64 s[98:99], exec, s[12:13]
	s_cbranch_scc1 .Lvd_15
	s_waitcnt vmcnt(8)
.Lvd_15:
	s_waitcnt lgkmcnt(0)
	s_setprio 1
	s_barrier
	v_mfma_f32_16x16x32_bf16 v[62:65], v[146:149], v[178:181], v[62:65]
	v_mfma_f32_16x16x32_bf16 v[58:61], v[154:157], v[178:181], v[58:61]
	v_mfma_f32_16x16x32_bf16 v[46:49], v[146:149], v[186:189], v[46:49]
	v_mfma_f32_16x16x32_bf16 v[42:45], v[154:157], v[186:189], v[42:45]
	v_mfma_f32_16x16x32_bf16 v[30:33], v[146:149], v[194:197], v[30:33]
	v_mfma_f32_16x16x32_bf16 v[26:29], v[154:157], v[194:197], v[26:29]
	v_mfma_f32_16x16x32_bf16 v[14:17], v[146:149], v[202:205], v[14:17]
	v_mfma_f32_16x16x32_bf16 v[10:13], v[154:157], v[202:205], v[10:13]
	v_mfma_f32_16x16x32_bf16 v[62:65], v[150:153], v[182:185], v[62:65]
	v_mfma_f32_16x16x32_bf16 v[58:61], v[158:161], v[182:185], v[58:61]
	v_mfma_f32_16x16x32_bf16 v[46:49], v[150:153], v[190:193], v[46:49]
	v_mfma_f32_16x16x32_bf16 v[42:45], v[158:161], v[190:193], v[42:45]
	v_mfma_f32_16x16x32_bf16 v[30:33], v[150:153], v[198:201], v[30:33]
	v_mfma_f32_16x16x32_bf16 v[26:29], v[158:161], v[198:201], v[26:29]
	v_mfma_f32_16x16x32_bf16 v[14:17], v[150:153], v[222:225], v[14:17]
	v_mfma_f32_16x16x32_bf16 v[10:13], v[158:161], v[222:225], v[10:13]
	v_mfma_f32_16x16x32_bf16 v[54:57], v[162:165], v[178:181], v[54:57]
	v_mfma_f32_16x16x32_bf16 v[50:53], v[170:173], v[178:181], v[50:53]
	v_mfma_f32_16x16x32_bf16 v[38:41], v[162:165], v[186:189], v[38:41]
	v_mfma_f32_16x16x32_bf16 v[34:37], v[170:173], v[186:189], v[34:37]
	v_mfma_f32_16x16x32_bf16 v[22:25], v[162:165], v[194:197], v[22:25]
	v_mfma_f32_16x16x32_bf16 v[18:21], v[170:173], v[194:197], v[18:21]
	v_mfma_f32_16x16x32_bf16 v[6:9], v[162:165], v[202:205], v[6:9]
	v_mfma_f32_16x16x32_bf16 v[2:5], v[170:173], v[202:205], v[2:5]
	v_mfma_f32_16x16x32_bf16 v[54:57], v[166:169], v[182:185], v[54:57]
	v_mfma_f32_16x16x32_bf16 v[50:53], v[174:177], v[182:185], v[50:53]
	v_mfma_f32_16x16x32_bf16 v[38:41], v[166:169], v[190:193], v[38:41]
	v_mfma_f32_16x16x32_bf16 v[34:37], v[174:177], v[190:193], v[34:37]
	v_mfma_f32_16x16x32_bf16 v[22:25], v[166:169], v[198:201], v[22:25]
	v_mfma_f32_16x16x32_bf16 v[18:21], v[174:177], v[198:201], v[18:21]
	v_mfma_f32_16x16x32_bf16 v[6:9], v[166:169], v[222:225], v[6:9]
	v_mfma_f32_16x16x32_bf16 v[2:5], v[174:177], v[222:225], v[2:5]
	s_barrier
	s_setprio 0
	s_waitcnt vmcnt(8)
	s_add_i32 s46, s46, 2
	s_add_u32 s17, s17, 0x100
	s_addc_u32 s42, s42, 0
	s_cmp_gt_u32 s46, 41
	s_mov_b64 s[18:19], s[2:3]
	s_cbranch_scc0 .LBB0_849
	s_and_b64 vcc, exec, s[12:13]
	s_cbranch_vccz .LBB0_852
	s_barrier
